# S5 stage-3 and EpiGlu residual stores merged pairwise into dwordx4 (permlane16_swap), on top of the gating rewrite
# speedup vs baseline: 1.0044x; 1.0044x over previous
.Ls5_epi:
	s_nop 2
	v_mov_b32_e32 v94, v162
	v_mov_b32_e32 v95, v163
	v_add_u32_e32 v158, 0x200, v158
	v_lshlrev_b32_e32 v92, 16, v94
	v_and_b32_e32 v93, 0xffff0000, v94
	v_pk_fma_f32 v[96:97], v[8:9], v[92:93], v[100:101]
	v_lshlrev_b32_e32 v94, 16, v95
	v_and_b32_e32 v93, 0x7fffffff, v97
	v_and_b32_e32 v92, 0x7fffffff, v96
	v_pk_fma_f32 v[92:93], v[92:93], s[80:81], 1.0 op_sel_hi:[1,0,0]
	v_and_b32_e32 v95, 0xffff0000, v95
	v_rcp_f32_e32 v98, v92
	v_rcp_f32_e32 v99, v93
	v_mov_b64_e32 v[92:93], s[54:55]
	v_cmp_gt_f32_e32 vcc, 0, v96
	v_pk_fma_f32 v[94:95], v[10:11], v[94:95], v[102:103]
	v_pk_fma_f32 v[100:101], v[98:99], s[50:51], v[92:93] op_sel_hi:[1,0,0]
	s_nop 0
	v_pk_fma_f32 v[100:101], v[98:99], v[100:101], s[76:77] op_sel_hi:[1,1,0]
	s_nop 0
	v_pk_fma_f32 v[100:101], v[98:99], v[100:101], s[78:79] op_sel_hi:[1,1,0]
	s_nop 0
	v_pk_fma_f32 v[100:101], v[98:99], v[100:101], s[2:3] op_sel_hi:[1,1,0]
	s_nop 0
	v_pk_mul_f32 v[98:99], v[98:99], v[100:101]
	v_pk_mul_f32 v[100:101], v[96:97], v[96:97]
	s_nop 0
	v_pk_mul_f32 v[100:101], v[100:101], s[0:1] op_sel_hi:[1,0]
	s_nop 0
	v_exp_f32_e32 v100, v100
	v_exp_f32_e32 v101, v101
	s_nop 0
	v_pk_mul_f32 v[98:99], v[100:101], v[98:99]
	s_nop 0
	v_pk_mul_f32 v[100:101], v[96:97], v[98:99]
	v_pk_fma_f32 v[98:99], v[96:97], v[98:99], v[96:97] neg_lo:[1,0,0] neg_hi:[1,0,0]
	v_and_b32_e32 v96, 0x7fffffff, v94
	v_cndmask_b32_e32 v100, v98, v100, vcc
	v_cmp_gt_f32_e32 vcc, 0, v97
	v_and_b32_e32 v97, 0x7fffffff, v95
	v_pk_fma_f32 v[96:97], v[96:97], s[80:81], 1.0 op_sel_hi:[1,0,0]
	v_cndmask_b32_e32 v101, v99, v101, vcc
	v_rcp_f32_e32 v96, v96
	v_rcp_f32_e32 v97, v97
	v_cmp_gt_f32_e32 vcc, 0, v94
	v_pk_fma_f32 v[98:99], v[96:97], s[50:51], v[92:93] op_sel_hi:[1,0,0]
	s_nop 0
	v_pk_fma_f32 v[98:99], v[96:97], v[98:99], s[76:77] op_sel_hi:[1,1,0]
	s_nop 0
	v_pk_fma_f32 v[98:99], v[96:97], v[98:99], s[78:79] op_sel_hi:[1,1,0]
	s_nop 0
	v_pk_fma_f32 v[98:99], v[96:97], v[98:99], s[2:3] op_sel_hi:[1,1,0]
	s_nop 0
	v_pk_mul_f32 v[96:97], v[96:97], v[98:99]
	v_pk_mul_f32 v[98:99], v[94:95], v[94:95]
	s_nop 0
	v_pk_mul_f32 v[98:99], v[98:99], s[0:1] op_sel_hi:[1,0]
	s_nop 0
	v_exp_f32_e32 v98, v98
	v_exp_f32_e32 v99, v99
	s_nop 0
	v_pk_mul_f32 v[96:97], v[98:99], v[96:97]
	s_nop 0
	v_pk_mul_f32 v[98:99], v[94:95], v[96:97]
	v_pk_fma_f32 v[96:97], v[94:95], v[96:97], v[94:95] neg_lo:[1,0,0] neg_hi:[1,0,0]
	v_cvt_pk_bf16_f32 v94, v100, v101
	s_nop 0
	v_cndmask_b32_e32 v96, v96, v98, vcc
	v_cmp_gt_f32_e32 vcc, 0, v95
	s_nop 1
	v_cndmask_b32_e32 v95, v97, v99, vcc
	v_cvt_pk_bf16_f32 v95, v96, v95
	v_lshl_add_u64 v[96:97], v[108:109], 0, s[4:5]
	v_mov_b32_e32 v240, v94
	v_mov_b32_e32 v241, v95
	v_mov_b32_e32 v244, v96
	v_mov_b32_e32 v245, v97
	v_mov_b32_e32 v94, v168
	v_mov_b32_e32 v95, v169
	v_add_u32_e32 v159, 0x200, v159
	v_lshlrev_b32_e32 v96, 16, v94
	v_and_b32_e32 v97, 0xffff0000, v94
	v_pk_fma_f32 v[88:89], v[8:9], v[96:97], v[88:89]
	s_nop 0
	v_and_b32_e32 v97, 0x7fffffff, v89
	v_and_b32_e32 v96, 0x7fffffff, v88
	v_pk_fma_f32 v[96:97], v[96:97], s[80:81], 1.0 op_sel_hi:[1,0,0]
	v_cmp_gt_f32_e32 vcc, 0, v88
	v_rcp_f32_e32 v96, v96
	v_rcp_f32_e32 v97, v97
	s_nop 0
	v_pk_fma_f32 v[98:99], v[96:97], s[50:51], v[92:93] op_sel_hi:[1,0,0]
	s_nop 0
	v_pk_fma_f32 v[98:99], v[96:97], v[98:99], s[76:77] op_sel_hi:[1,1,0]
	s_nop 0
	v_pk_fma_f32 v[98:99], v[96:97], v[98:99], s[78:79] op_sel_hi:[1,1,0]
	s_nop 0
	v_pk_fma_f32 v[98:99], v[96:97], v[98:99], s[2:3] op_sel_hi:[1,1,0]
	s_nop 0
	v_pk_mul_f32 v[96:97], v[96:97], v[98:99]
	v_pk_mul_f32 v[98:99], v[88:89], v[88:89]
	s_nop 0
	v_pk_mul_f32 v[98:99], v[98:99], s[0:1] op_sel_hi:[1,0]
	s_nop 0
	v_exp_f32_e32 v98, v98
	v_exp_f32_e32 v99, v99
	s_nop 0
	v_pk_mul_f32 v[96:97], v[98:99], v[96:97]
	s_nop 0
	v_pk_mul_f32 v[98:99], v[88:89], v[96:97]
	v_pk_fma_f32 v[96:97], v[88:89], v[96:97], v[88:89] neg_lo:[1,0,0] neg_hi:[1,0,0]
	v_lshlrev_b32_e32 v88, 16, v95
	v_cndmask_b32_e32 v94, v96, v98, vcc
	v_cmp_gt_f32_e32 vcc, 0, v89
	v_and_b32_e32 v89, 0xffff0000, v95
	v_pk_fma_f32 v[88:89], v[10:11], v[88:89], v[90:91]
	v_cndmask_b32_e32 v96, v97, v99, vcc
	v_and_b32_e32 v91, 0x7fffffff, v89
	v_and_b32_e32 v90, 0x7fffffff, v88
	v_pk_fma_f32 v[90:91], v[90:91], s[80:81], 1.0 op_sel_hi:[1,0,0]
	v_cmp_gt_f32_e32 vcc, 0, v88
	v_rcp_f32_e32 v90, v90
	v_rcp_f32_e32 v91, v91
	s_nop 0
	v_pk_fma_f32 v[92:93], v[90:91], s[50:51], v[92:93] op_sel_hi:[1,0,0]
	s_nop 0
	v_pk_fma_f32 v[92:93], v[90:91], v[92:93], s[76:77] op_sel_hi:[1,1,0]
	s_nop 0
	v_pk_fma_f32 v[92:93], v[90:91], v[92:93], s[78:79] op_sel_hi:[1,1,0]
	s_nop 0
	v_pk_fma_f32 v[92:93], v[90:91], v[92:93], s[2:3] op_sel_hi:[1,1,0]
	s_nop 0
	v_pk_mul_f32 v[90:91], v[90:91], v[92:93]
	v_pk_mul_f32 v[92:93], v[88:89], v[88:89]
	s_nop 0
	v_pk_mul_f32 v[92:93], v[92:93], s[0:1] op_sel_hi:[1,0]
	s_nop 0
	v_exp_f32_e32 v92, v92
	v_exp_f32_e32 v93, v93
	s_nop 0
	v_pk_mul_f32 v[90:91], v[92:93], v[90:91]
	s_nop 0
	v_pk_mul_f32 v[92:93], v[88:89], v[90:91]
	v_pk_fma_f32 v[90:91], v[88:89], v[90:91], v[88:89] neg_lo:[1,0,0] neg_hi:[1,0,0]
	v_cvt_pk_bf16_f32 v88, v94, v96
	s_nop 0
	v_cndmask_b32_e32 v90, v90, v92, vcc
	v_cmp_gt_f32_e32 vcc, 0, v89
	s_nop 1
	v_cndmask_b32_e32 v89, v91, v93, vcc
	v_cvt_pk_bf16_f32 v89, v90, v89
	v_lshl_add_u64 v[90:91], v[106:107], 0, s[4:5]
	v_mov_b32_e32 v242, v88
	v_mov_b32_e32 v243, v89
	v_mbcnt_lo_u32_b32 v246, -1, 0
	v_mbcnt_hi_u32_b32 v246, -1, v246
	v_and_b32_e32 v246, 16, v246
	v_cmp_ne_u32_e32 vcc, 0, v246
	v_permlane16_swap_b32_e32 v240, v242
	v_permlane16_swap_b32_e32 v241, v243
	v_cndmask_b32_e32 v244, v244, v90, vcc
	v_cndmask_b32_e32 v245, v245, v91, vcc
	v_lshrrev_b32_e32 v246, 1, v246
	v_sub_co_u32_e32 v244, vcc, v244, v246
	v_subbrev_co_u32_e32 v245, vcc, 0, v245, vcc
	s_add_u32 s4, s4, 0x100000
	s_addc_u32 s5, s5, 0
	s_cmp_eq_u32 s4, 0x400000
	global_store_dwordx4 v[244:245], v[240:243], off
	s_cbranch_scc1 .LBB0_1391

.LBB0_1529:
	s_mov_b32 s0, s40
	s_lshl_b32 s1, s22, 7
	v_mov_b32_e32 v154, v182
	v_mov_b32_e32 v160, v183
	s_or_b32 s1, s1, s48
	s_lshl_b32 s0, s0, 8
	v_lshl_add_u32 v152, v160, 2, s1
	v_ashrrev_i32_e32 v153, 31, v152
	v_lshlrev_b64 v[80:81], 2, v[152:153]
	v_lshl_add_u64 v[82:83], s[12:13], 0, v[80:81]
	v_lshl_add_u64 v[84:85], s[26:27], 0, v[80:81]
	global_load_dwordx4 v[100:103], v[84:85], off
	global_load_dwordx4 v[92:95], v[82:83], off
	s_nop 0
	global_load_dwordx4 v[80:83], v[82:83], off offset:256
	s_nop 0
	global_load_dwordx4 v[84:87], v[84:85], off offset:256
	s_add_i32 s0, s0, s45
	v_add_u32_e32 v156, s0, v154
	v_lshlrev_b64 v[190:191], 1, v[152:153]
	v_ashrrev_i32_e32 v157, 31, v156
	v_lshl_add_u64 v[154:155], s[16:17], 0, v[190:191]
	v_lshlrev_b64 v[192:193], 12, v[156:157]
	v_lshl_add_u64 v[158:159], v[154:155], 0, v[192:193]
	v_mbcnt_lo_u32_b32 v214, -1, 0
	v_mbcnt_hi_u32_b32 v214, -1, v214
	v_lshrrev_b32_e32 v214, 4, v214
	v_and_b32_e32 v214, 1, v214
	v_mul_u32_u24_e32 v214, 0x78, v214
	v_mov_b32_e32 v215, 0
	global_load_dwordx2 v[194:195], v[158:159], off
	global_load_dwordx2 v[196:197], v[158:159], off offset:128
	v_add_u32_e32 v172, 16, v156
	v_add_u32_e32 v166, 32, v156
	v_add_u32_e32 v158, 48, v156
	v_ashrrev_i32_e32 v173, 31, v172
	v_ashrrev_i32_e32 v167, 31, v166
	v_ashrrev_i32_e32 v159, 31, v158
	v_lshlrev_b64 v[176:177], 12, v[172:173]
	v_lshlrev_b64 v[168:169], 12, v[166:167]
	v_cmp_eq_u32_e32 vcc, 0, v160
	v_lshlrev_b64 v[160:161], 12, v[158:159]
	v_lshl_add_u64 v[162:163], v[154:155], 0, v[176:177]
	v_lshl_add_u64 v[164:165], v[154:155], 0, v[168:169]
	v_lshl_add_u64 v[198:199], v[154:155], 0, v[160:161]
	global_load_dwordx2 v[180:181], v[162:163], off
	global_load_dwordx2 v[178:179], v[162:163], off offset:128
	global_load_dwordx2 v[174:175], v[164:165], off
	global_load_dwordx2 v[170:171], v[164:165], off offset:128
	s_nop 0
	global_load_dwordx2 v[164:165], v[198:199], off
	global_load_dwordx2 v[162:163], v[198:199], off offset:128
	s_lshl_b32 s0, s22, 2
	s_ashr_i32 s1, s0, 31
	s_waitcnt vmcnt(0)
	v_add_f32_e32 v141, v141, v101
	v_add_f32_e32 v143, v143, v103
	v_add_f32_e32 v140, v140, v100
	v_add_f32_e32 v142, v142, v102
	v_add_f32_e32 v132, v132, v84
	v_mul_f32_e32 v141, 0xbfb8aa3b, v141
	v_mul_f32_e32 v143, 0xbfb8aa3b, v143
	v_mul_f32_e32 v140, 0xbfb8aa3b, v140
	v_mul_f32_e32 v142, 0xbfb8aa3b, v142
	v_mul_f32_e32 v132, 0xbfb8aa3b, v132
	v_exp_f32_e32 v141, v141
	v_exp_f32_e32 v143, v143
	v_exp_f32_e32 v140, v140
	v_exp_f32_e32 v142, v142
	v_exp_f32_e32 v132, v132
	v_add_f32_e32 v141, 1.0, v141
	v_add_f32_e32 v143, 1.0, v143
	v_add_f32_e32 v140, 1.0, v140
	v_add_f32_e32 v142, 1.0, v142
	v_add_f32_e32 v132, 1.0, v132
	v_rcp_f32_e32 v141, v141
	v_rcp_f32_e32 v143, v143
	v_add_f32_e32 v133, v133, v85
	v_rcp_f32_e32 v140, v140
	v_rcp_f32_e32 v142, v142
	v_rcp_f32_e32 v132, v132
	v_mul_f32_e32 v133, 0xbfb8aa3b, v133
	v_add_f32_e32 v137, v137, v93
	v_add_f32_e32 v139, v139, v95
	v_lshlrev_b32_e32 v189, 16, v194
	v_and_b32_e32 v194, 0xffff0000, v194
	v_lshlrev_b32_e32 v198, 16, v195
	v_and_b32_e32 v195, 0xffff0000, v195
	v_exp_f32_e32 v133, v133
	v_add_f32_e32 v136, v136, v92
	v_add_f32_e32 v138, v138, v94
	v_add_f32_e32 v128, v128, v80
	v_lshlrev_b32_e32 v199, 16, v196
	v_fmac_f32_e32 v194, v137, v141
	v_fmac_f32_e32 v195, v139, v143
	v_fmac_f32_e32 v189, v136, v140
	v_fmac_f32_e32 v198, v138, v142
	v_fmac_f32_e32 v199, v128, v132
	v_mul_f32_e32 v128, v194, v194
	v_mul_f32_e32 v132, v195, v195
	v_add_f32_e32 v134, v134, v86
	v_fmac_f32_e32 v128, v189, v189
	v_fmac_f32_e32 v132, v198, v198
	v_add_f32_e32 v133, 1.0, v133
	v_add_f32_e32 v128, v128, v132
	v_mul_f32_e32 v132, 0xbfb8aa3b, v134
	v_add_f32_e32 v134, v135, v87
	v_rcp_f32_e32 v133, v133
	v_exp_f32_e32 v132, v132
	v_mul_f32_e32 v134, 0xbfb8aa3b, v134
	v_exp_f32_e32 v134, v134
	v_add_f32_e32 v129, v129, v81
	v_and_b32_e32 v196, 0xffff0000, v196
	v_fmac_f32_e32 v196, v129, v133
	v_add_f32_e32 v129, 1.0, v132
	v_rcp_f32_e32 v129, v129
	v_add_f32_e32 v132, 1.0, v134
	v_rcp_f32_e32 v132, v132
	v_lshlrev_b32_e32 v200, 16, v197
	v_add_f32_e32 v130, v130, v82
	v_and_b32_e32 v197, 0xffff0000, v197
	v_fmac_f32_e32 v200, v130, v129
	v_add_f32_e32 v129, v131, v83
	v_fmac_f32_e32 v197, v129, v132
	v_mul_f32_e32 v129, v196, v196
	v_mul_f32_e32 v130, v197, v197
	v_fmac_f32_e32 v129, v199, v199
	v_fmac_f32_e32 v130, v200, v200
	v_add_f32_e32 v129, v129, v130
	v_and_b32_e32 v130, 64, v188
	v_add_f32_e32 v129, v128, v129
	v_xor_b32_e32 v128, 16, v188
	v_add_u32_e32 v136, 64, v130
	v_cmp_lt_i32_e64 s[2:3], v128, v136
	v_lshl_add_u64 v[130:131], s[16:17], 0, v[192:193]
	v_lshl_add_u64 v[134:135], v[130:131], 0, v[190:191]
	v_cndmask_b32_e64 v128, v188, v128, s[2:3]
	v_lshlrev_b32_e32 v128, 2, v128
	v_mov_b32_e32 v137, v129
	s_nop 1
	v_permlane16_swap_b32_e32 v137, v129
	v_cvt_pk_bf16_f32 v132, v189, v194
	v_cvt_pk_bf16_f32 v133, v198, v195
	v_mov_b32_e32 v204, v132
	v_mov_b32_e32 v205, v133
	v_cvt_pk_bf16_f32 v132, v199, v196
	s_waitcnt lgkmcnt(0)
	v_add_f32_e32 v130, v129, v137
	v_xor_b32_e32 v129, 32, v188
	v_cmp_lt_i32_e64 s[2:3], v129, v136
	v_cvt_pk_bf16_f32 v133, v200, v197
	v_mov_b32_e32 v206, v132
	v_mov_b32_e32 v207, v133
	v_lshl_add_u64 v[212:213], v[134:135], 0, v[214:215]
	s_nop 0
	v_permlane16_swap_b32_e32 v204, v206
	v_permlane16_swap_b32_e32 v205, v207
	global_store_dwordx4 v[212:213], v[204:207], off
	s_nop 0
	v_cndmask_b32_e64 v129, v188, v129, s[2:3]
	v_lshlrev_b32_e32 v129, 2, v129
	v_mov_b32_e32 v131, v130
	s_nop 1
	v_permlane32_swap_b32_e32 v131, v130
	s_and_saveexec_b64 s[2:3], vcc
	s_cbranch_execz .LBB0_1531
	s_waitcnt lgkmcnt(0)
	v_add_f32_e32 v132, v130, v131
	v_lshlrev_b64 v[130:131], 8, v[156:157]
	v_lshl_add_u64 v[130:131], s[18:19], 0, v[130:131]
	v_lshl_add_u64 v[130:131], s[0:1], 2, v[130:131]
	s_lshl_b32 s22, s44, 2
	v_lshl_add_u64 v[130:131], v[130:131], 0, s[22:23]
	global_store_dword v[130:131], v132, off
.LBB0_1531:
	s_or_b64 exec, exec, s[2:3]
	v_add_f32_e32 v124, v124, v100
	v_mul_f32_e32 v124, 0xbfb8aa3b, v124
	v_exp_f32_e32 v124, v124
	v_add_f32_e32 v125, v125, v101
	v_mul_f32_e32 v125, 0xbfb8aa3b, v125
	v_exp_f32_e32 v125, v125
	v_add_f32_e32 v124, 1.0, v124
	v_rcp_f32_e32 v124, v124
	v_lshlrev_b32_e32 v130, 16, v180
	v_add_f32_e32 v120, v120, v92
	s_waitcnt lgkmcnt(0)
	v_and_b32_e32 v131, 0xffff0000, v180
	v_fmac_f32_e32 v130, v120, v124
	v_add_f32_e32 v124, v126, v102
	v_add_f32_e32 v120, 1.0, v125
	v_mul_f32_e32 v124, 0xbfb8aa3b, v124
	v_add_f32_e32 v125, v127, v103
	v_rcp_f32_e32 v120, v120
	v_exp_f32_e32 v124, v124
	v_mul_f32_e32 v125, 0xbfb8aa3b, v125
	v_exp_f32_e32 v125, v125
	v_add_f32_e32 v121, v121, v93
	v_add_f32_e32 v116, v116, v84
	v_fmac_f32_e32 v131, v121, v120
	v_add_f32_e32 v120, 1.0, v124
	v_mul_f32_e32 v116, 0xbfb8aa3b, v116
	v_rcp_f32_e32 v120, v120
	v_add_f32_e32 v121, 1.0, v125
	v_exp_f32_e32 v116, v116
	v_rcp_f32_e32 v121, v121
	v_lshlrev_b32_e32 v132, 16, v181
	v_add_f32_e32 v122, v122, v94
	v_and_b32_e32 v133, 0xffff0000, v181
	v_fmac_f32_e32 v132, v122, v120
	v_add_f32_e32 v120, v123, v95
	v_add_f32_e32 v116, 1.0, v116
	v_add_f32_e32 v117, v117, v85
	v_fmac_f32_e32 v133, v120, v121
	v_rcp_f32_e32 v116, v116
	v_mul_f32_e32 v117, 0xbfb8aa3b, v117
	v_mul_f32_e32 v120, v131, v131
	v_mul_f32_e32 v121, v133, v133
	v_exp_f32_e32 v117, v117
	v_fmac_f32_e32 v120, v130, v130
	v_fmac_f32_e32 v121, v132, v132
	v_add_f32_e32 v120, v120, v121
	v_lshlrev_b32_e32 v121, 16, v178
	v_add_f32_e32 v112, v112, v80
	v_fmac_f32_e32 v121, v112, v116
	v_add_f32_e32 v116, v118, v86
	v_add_f32_e32 v112, 1.0, v117
	v_mul_f32_e32 v116, 0xbfb8aa3b, v116
	v_add_f32_e32 v117, v119, v87
	v_rcp_f32_e32 v112, v112
	v_exp_f32_e32 v116, v116
	v_mul_f32_e32 v117, 0xbfb8aa3b, v117
	v_exp_f32_e32 v117, v117
	v_and_b32_e32 v122, 0xffff0000, v178
	v_add_f32_e32 v113, v113, v81
	v_fmac_f32_e32 v122, v113, v112
	v_add_f32_e32 v112, 1.0, v116
	v_rcp_f32_e32 v112, v112
	v_add_f32_e32 v113, 1.0, v117
	v_rcp_f32_e32 v113, v113
	v_lshlrev_b32_e32 v123, 16, v179
	v_add_f32_e32 v114, v114, v82
	v_and_b32_e32 v124, 0xffff0000, v179
	v_fmac_f32_e32 v123, v114, v112
	v_add_f32_e32 v112, v115, v83
	v_fmac_f32_e32 v124, v112, v113
	v_mul_f32_e32 v112, v122, v122
	v_mul_f32_e32 v113, v124, v124
	v_fmac_f32_e32 v112, v121, v121
	v_fmac_f32_e32 v113, v123, v123
	v_add_f32_e32 v112, v112, v113
	v_add_f32_e32 v118, v120, v112
	v_mov_b32_e32 v119, v118
	s_nop 1
	v_permlane16_swap_b32_e32 v119, v118
	v_lshl_add_u64 v[112:113], s[16:17], 0, v[176:177]
	v_lshl_add_u64 v[116:117], v[152:153], 1, v[112:113]
	v_cvt_pk_bf16_f32 v114, v130, v131
	v_cvt_pk_bf16_f32 v115, v132, v133
	s_waitcnt lgkmcnt(0)
	v_add_f32_e32 v112, v118, v119
	v_mov_b32_e32 v113, v112
	s_nop 1
	v_permlane32_swap_b32_e32 v113, v112
	v_mov_b32_e32 v208, v114
	v_mov_b32_e32 v209, v115
	v_cvt_pk_bf16_f32 v114, v121, v122
	v_cvt_pk_bf16_f32 v115, v123, v124
	v_mov_b32_e32 v210, v114
	v_mov_b32_e32 v211, v115
	v_lshl_add_u64 v[212:213], v[116:117], 0, v[214:215]
	s_nop 0
	v_permlane16_swap_b32_e32 v208, v210
	v_permlane16_swap_b32_e32 v209, v211
	global_store_dwordx4 v[212:213], v[208:211], off
	s_and_saveexec_b64 s[2:3], vcc
	s_cbranch_execz .LBB0_1533
	s_waitcnt lgkmcnt(0)
	v_add_f32_e32 v114, v112, v113
	v_lshlrev_b64 v[112:113], 8, v[172:173]
	v_lshl_add_u64 v[112:113], s[18:19], 0, v[112:113]
	v_lshl_add_u64 v[112:113], s[0:1], 2, v[112:113]
	s_lshl_b32 s22, s44, 2
	v_lshl_add_u64 v[112:113], v[112:113], 0, s[22:23]
	global_store_dword v[112:113], v114, off
.LBB0_1533:
	s_or_b64 exec, exec, s[2:3]
	v_add_f32_e32 v108, v108, v100
	v_mul_f32_e32 v108, 0xbfb8aa3b, v108
	v_exp_f32_e32 v108, v108
	v_add_f32_e32 v109, v109, v101
	v_mul_f32_e32 v109, 0xbfb8aa3b, v109
	v_exp_f32_e32 v109, v109
	v_add_f32_e32 v108, 1.0, v108
	v_rcp_f32_e32 v108, v108
	v_lshlrev_b32_e32 v112, 16, v174
	v_add_f32_e32 v104, v104, v92
	s_waitcnt lgkmcnt(0)
	v_and_b32_e32 v113, 0xffff0000, v174
	v_fmac_f32_e32 v112, v104, v108
	v_add_f32_e32 v108, v110, v102
	v_add_f32_e32 v104, 1.0, v109
	v_mul_f32_e32 v108, 0xbfb8aa3b, v108
	v_add_f32_e32 v109, v111, v103
	v_rcp_f32_e32 v104, v104
	v_exp_f32_e32 v108, v108
	v_mul_f32_e32 v109, 0xbfb8aa3b, v109
	v_exp_f32_e32 v109, v109
	v_add_f32_e32 v105, v105, v93
	v_add_f32_e32 v96, v96, v84
	v_fmac_f32_e32 v113, v105, v104
	v_add_f32_e32 v104, 1.0, v108
	v_mul_f32_e32 v96, 0xbfb8aa3b, v96
	v_rcp_f32_e32 v104, v104
	v_add_f32_e32 v105, 1.0, v109
	v_exp_f32_e32 v96, v96
	v_rcp_f32_e32 v105, v105
	v_lshlrev_b32_e32 v114, 16, v175
	v_add_f32_e32 v106, v106, v94
	v_and_b32_e32 v115, 0xffff0000, v175
	v_fmac_f32_e32 v114, v106, v104
	v_add_f32_e32 v104, v107, v95
	v_add_f32_e32 v96, 1.0, v96
	v_add_f32_e32 v97, v97, v85
	v_fmac_f32_e32 v115, v104, v105
	v_rcp_f32_e32 v96, v96
	v_mul_f32_e32 v97, 0xbfb8aa3b, v97
	v_mul_f32_e32 v104, v113, v113
	v_mul_f32_e32 v105, v115, v115
	v_exp_f32_e32 v97, v97
	v_fmac_f32_e32 v104, v112, v112
	v_fmac_f32_e32 v105, v114, v114
	v_add_f32_e32 v104, v104, v105
	v_lshlrev_b32_e32 v105, 16, v170
	v_add_f32_e32 v88, v88, v80
	v_fmac_f32_e32 v105, v88, v96
	v_add_f32_e32 v96, v98, v86
	v_add_f32_e32 v88, 1.0, v97
	v_mul_f32_e32 v96, 0xbfb8aa3b, v96
	v_add_f32_e32 v97, v99, v87
	v_rcp_f32_e32 v88, v88
	v_exp_f32_e32 v96, v96
	v_mul_f32_e32 v97, 0xbfb8aa3b, v97
	v_exp_f32_e32 v97, v97
	v_and_b32_e32 v106, 0xffff0000, v170
	v_add_f32_e32 v89, v89, v81
	v_fmac_f32_e32 v106, v89, v88
	v_add_f32_e32 v88, 1.0, v96
	v_rcp_f32_e32 v88, v88
	v_add_f32_e32 v89, 1.0, v97
	v_rcp_f32_e32 v89, v89
	v_lshlrev_b32_e32 v107, 16, v171
	v_add_f32_e32 v90, v90, v82
	v_and_b32_e32 v108, 0xffff0000, v171
	v_fmac_f32_e32 v107, v90, v88
	v_add_f32_e32 v88, v91, v83
	v_fmac_f32_e32 v108, v88, v89
	v_mul_f32_e32 v88, v106, v106
	v_mul_f32_e32 v89, v108, v108
	v_fmac_f32_e32 v88, v105, v105
	v_fmac_f32_e32 v89, v107, v107
	v_add_f32_e32 v88, v88, v89
	v_add_f32_e32 v98, v104, v88
	v_mov_b32_e32 v99, v98
	s_nop 1
	v_permlane16_swap_b32_e32 v99, v98
	v_lshl_add_u64 v[88:89], s[16:17], 0, v[168:169]
	v_lshl_add_u64 v[96:97], v[152:153], 1, v[88:89]
	v_cvt_pk_bf16_f32 v90, v112, v113
	v_cvt_pk_bf16_f32 v91, v114, v115
	s_waitcnt lgkmcnt(0)
	v_add_f32_e32 v88, v98, v99
	v_mov_b32_e32 v89, v88
	s_nop 1
	v_permlane32_swap_b32_e32 v89, v88
	v_mov_b32_e32 v204, v90
	v_mov_b32_e32 v205, v91
	v_cvt_pk_bf16_f32 v90, v105, v106
	v_cvt_pk_bf16_f32 v91, v107, v108
	v_mov_b32_e32 v206, v90
	v_mov_b32_e32 v207, v91
	v_lshl_add_u64 v[212:213], v[96:97], 0, v[214:215]
	s_nop 0
	v_permlane16_swap_b32_e32 v204, v206
	v_permlane16_swap_b32_e32 v205, v207
	global_store_dwordx4 v[212:213], v[204:207], off
	s_and_saveexec_b64 s[2:3], vcc
	s_cbranch_execz .LBB0_1535
	s_waitcnt lgkmcnt(0)
	v_add_f32_e32 v90, v88, v89
	v_lshlrev_b64 v[88:89], 8, v[166:167]
	v_lshl_add_u64 v[88:89], s[18:19], 0, v[88:89]
	v_lshl_add_u64 v[88:89], s[0:1], 2, v[88:89]
	s_lshl_b32 s22, s44, 2
	v_lshl_add_u64 v[88:89], v[88:89], 0, s[22:23]
	global_store_dword v[88:89], v90, off
.LBB0_1535:
	s_or_b64 exec, exec, s[2:3]
	v_add_f32_e32 v76, v76, v100
	v_mul_f32_e32 v76, 0xbfb8aa3b, v76
	v_exp_f32_e32 v76, v76
	v_add_f32_e32 v77, v77, v101
	v_mul_f32_e32 v77, 0xbfb8aa3b, v77
	v_exp_f32_e32 v77, v77
	v_add_f32_e32 v76, 1.0, v76
	v_rcp_f32_e32 v76, v76
	v_lshlrev_b32_e32 v88, 16, v164
	v_add_f32_e32 v72, v72, v92
	s_waitcnt lgkmcnt(0)
	v_and_b32_e32 v89, 0xffff0000, v164
	v_fmac_f32_e32 v88, v72, v76
	v_add_f32_e32 v76, v78, v102
	v_add_f32_e32 v72, 1.0, v77
	v_mul_f32_e32 v76, 0xbfb8aa3b, v76
	v_add_f32_e32 v77, v79, v103
	v_rcp_f32_e32 v72, v72
	v_exp_f32_e32 v76, v76
	v_mul_f32_e32 v77, 0xbfb8aa3b, v77
	v_exp_f32_e32 v77, v77
	v_add_f32_e32 v73, v73, v93
	v_add_f32_e32 v68, v68, v84
	v_fmac_f32_e32 v89, v73, v72
	v_add_f32_e32 v72, 1.0, v76
	v_mul_f32_e32 v68, 0xbfb8aa3b, v68
	v_rcp_f32_e32 v72, v72
	v_add_f32_e32 v73, 1.0, v77
	v_exp_f32_e32 v68, v68
	v_rcp_f32_e32 v73, v73
	v_lshlrev_b32_e32 v90, 16, v165
	v_add_f32_e32 v74, v74, v94
	v_and_b32_e32 v91, 0xffff0000, v165
	v_fmac_f32_e32 v90, v74, v72
	v_add_f32_e32 v72, v75, v95
	v_add_f32_e32 v68, 1.0, v68
	v_add_f32_e32 v69, v69, v85
	v_fmac_f32_e32 v91, v72, v73
	v_rcp_f32_e32 v68, v68
	v_mul_f32_e32 v69, 0xbfb8aa3b, v69
	v_mul_f32_e32 v72, v89, v89
	v_mul_f32_e32 v73, v91, v91
	v_exp_f32_e32 v69, v69
	v_fmac_f32_e32 v72, v88, v88
	v_fmac_f32_e32 v73, v90, v90
	v_add_f32_e32 v72, v72, v73
	v_lshlrev_b32_e32 v73, 16, v162
	v_add_f32_e32 v64, v64, v80
	v_fmac_f32_e32 v73, v64, v68
	v_add_f32_e32 v68, v70, v86
	v_add_f32_e32 v64, 1.0, v69
	v_mul_f32_e32 v68, 0xbfb8aa3b, v68
	v_add_f32_e32 v69, v71, v87
	v_rcp_f32_e32 v64, v64
	v_exp_f32_e32 v68, v68
	v_mul_f32_e32 v69, 0xbfb8aa3b, v69
	v_exp_f32_e32 v69, v69
	v_and_b32_e32 v74, 0xffff0000, v162
	v_add_f32_e32 v65, v65, v81
	v_fmac_f32_e32 v74, v65, v64
	v_add_f32_e32 v64, 1.0, v68
	v_rcp_f32_e32 v64, v64
	v_add_f32_e32 v65, 1.0, v69
	v_rcp_f32_e32 v65, v65
	v_lshlrev_b32_e32 v75, 16, v163
	v_add_f32_e32 v66, v66, v82
	v_and_b32_e32 v76, 0xffff0000, v163
	v_fmac_f32_e32 v75, v66, v64
	v_add_f32_e32 v64, v67, v83
	v_fmac_f32_e32 v76, v64, v65
	v_mul_f32_e32 v64, v74, v74
	v_mul_f32_e32 v65, v76, v76
	v_fmac_f32_e32 v64, v73, v73
	v_fmac_f32_e32 v65, v75, v75
	v_add_f32_e32 v64, v64, v65
	v_add_f32_e32 v70, v72, v64
	v_mov_b32_e32 v71, v70
	s_nop 1
	v_permlane16_swap_b32_e32 v71, v70
	v_lshl_add_u64 v[64:65], s[16:17], 0, v[160:161]
	v_lshl_add_u64 v[68:69], v[152:153], 1, v[64:65]
	v_cvt_pk_bf16_f32 v66, v88, v89
	v_cvt_pk_bf16_f32 v67, v90, v91
	s_waitcnt lgkmcnt(0)
	v_add_f32_e32 v64, v70, v71
	v_mov_b32_e32 v65, v64
	s_nop 1
	v_permlane32_swap_b32_e32 v65, v64
	v_mov_b32_e32 v208, v66
	v_mov_b32_e32 v209, v67
	v_cvt_pk_bf16_f32 v66, v73, v74
	v_cvt_pk_bf16_f32 v67, v75, v76
	v_mov_b32_e32 v210, v66
	v_mov_b32_e32 v211, v67
	v_lshl_add_u64 v[212:213], v[68:69], 0, v[214:215]
	s_nop 0
	v_permlane16_swap_b32_e32 v208, v210
	v_permlane16_swap_b32_e32 v209, v211
	global_store_dwordx4 v[212:213], v[208:211], off
	s_and_saveexec_b64 s[2:3], vcc
	s_cbranch_execz .LBB0_1537
	s_waitcnt lgkmcnt(0)
	v_add_f32_e32 v66, v64, v65
	v_lshlrev_b64 v[64:65], 8, v[158:159]
	v_lshl_add_u64 v[64:65], s[18:19], 0, v[64:65]
	v_lshl_add_u64 v[64:65], s[0:1], 2, v[64:65]
	s_lshl_b32 s22, s44, 2
	v_lshl_add_u64 v[64:65], v[64:65], 0, s[22:23]
	global_store_dword v[64:65], v66, off
.LBB0_1537:
	s_or_b64 exec, exec, s[2:3]
	v_add_u32_e32 v78, 0x80, v156
	v_ashrrev_i32_e32 v79, 31, v78
	v_lshlrev_b64 v[90:91], 12, v[78:79]
	s_waitcnt lgkmcnt(0)
	v_lshl_add_u64 v[64:65], v[154:155], 0, v[90:91]
	global_load_dwordx2 v[96:97], v[64:65], off
	global_load_dwordx2 v[98:99], v[64:65], off offset:128
	v_add_u32_e32 v70, 0x90, v156
	v_add_u32_e32 v66, 0xa0, v156
	v_add_u32_e32 v64, 0xb0, v156
	v_ashrrev_i32_e32 v71, 31, v70
	v_ashrrev_i32_e32 v67, 31, v66
	v_add_f32_e32 v110, v62, v102
	v_add_f32_e32 v112, v63, v103
	v_ashrrev_i32_e32 v65, 31, v64
	v_lshlrev_b64 v[74:75], 12, v[70:71]
	v_lshlrev_b64 v[62:63], 12, v[66:67]
	v_add_f32_e32 v106, v60, v100
	v_add_f32_e32 v107, v56, v92
	v_add_f32_e32 v108, v61, v101
	v_add_f32_e32 v109, v57, v93
	v_add_f32_e32 v111, v58, v94
	v_add_f32_e32 v113, v59, v95
	v_lshlrev_b64 v[56:57], 12, v[64:65]
	v_lshl_add_u64 v[58:59], v[154:155], 0, v[74:75]
	v_lshl_add_u64 v[60:61], v[154:155], 0, v[62:63]
	v_lshl_add_u64 v[104:105], v[154:155], 0, v[56:57]
	global_load_dwordx2 v[88:89], v[58:59], off
	global_load_dwordx2 v[76:77], v[58:59], off offset:128
	global_load_dwordx2 v[72:73], v[60:61], off
	global_load_dwordx2 v[68:69], v[60:61], off offset:128
	s_nop 0
	global_load_dwordx2 v[60:61], v[104:105], off
	global_load_dwordx2 v[58:59], v[104:105], off offset:128
	v_add_f32_e32 v52, v52, v84
	v_add_f32_e32 v53, v53, v85
	v_mul_f32_e32 v105, 0xbfb8aa3b, v108
	v_mul_f32_e32 v108, 0xbfb8aa3b, v112
	v_mul_f32_e32 v104, 0xbfb8aa3b, v106
	v_mul_f32_e32 v106, 0xbfb8aa3b, v110
	v_mul_f32_e32 v52, 0xbfb8aa3b, v52
	v_mul_f32_e32 v53, 0xbfb8aa3b, v53
	v_exp_f32_e32 v105, v105
	v_exp_f32_e32 v108, v108
	v_exp_f32_e32 v104, v104
	v_exp_f32_e32 v106, v106
	v_exp_f32_e32 v52, v52
	v_exp_f32_e32 v53, v53
	v_add_f32_e32 v105, 1.0, v105
	v_add_f32_e32 v108, 1.0, v108
	v_add_f32_e32 v54, v54, v86
	v_add_f32_e32 v104, 1.0, v104
	v_add_f32_e32 v106, 1.0, v106
	v_add_f32_e32 v52, 1.0, v52
	v_add_f32_e32 v53, 1.0, v53
	v_rcp_f32_e32 v105, v105
	v_rcp_f32_e32 v108, v108
	v_add_f32_e32 v55, v55, v87
	v_mul_f32_e32 v54, 0xbfb8aa3b, v54
	v_rcp_f32_e32 v104, v104
	v_rcp_f32_e32 v106, v106
	v_rcp_f32_e32 v52, v52
	v_rcp_f32_e32 v53, v53
	v_mul_f32_e32 v55, 0xbfb8aa3b, v55
	v_exp_f32_e32 v54, v54
	v_exp_f32_e32 v55, v55
	v_add_f32_e32 v48, v48, v80
	v_add_f32_e32 v49, v49, v81
	v_add_f32_e32 v54, 1.0, v54
	v_rcp_f32_e32 v54, v54
	v_add_f32_e32 v50, v50, v82
	s_waitcnt vmcnt(7)
	v_lshlrev_b32_e32 v110, 16, v96
	v_and_b32_e32 v96, 0xffff0000, v96
	v_lshlrev_b32_e32 v112, 16, v97
	v_and_b32_e32 v97, 0xffff0000, v97
	s_waitcnt vmcnt(6)
	v_lshlrev_b32_e32 v114, 16, v98
	v_and_b32_e32 v98, 0xffff0000, v98
	v_fmac_f32_e32 v96, v109, v105
	v_fmac_f32_e32 v97, v113, v108
	v_fmac_f32_e32 v110, v107, v104
	v_fmac_f32_e32 v112, v111, v106
	v_fmac_f32_e32 v114, v48, v52
	v_fmac_f32_e32 v98, v49, v53
	v_mul_f32_e32 v48, v96, v96
	v_mul_f32_e32 v49, v97, v97
	v_fmac_f32_e32 v48, v110, v110
	v_fmac_f32_e32 v49, v112, v112
	v_add_f32_e32 v48, v48, v49
	v_add_f32_e32 v49, 1.0, v55
	v_rcp_f32_e32 v49, v49
	v_lshlrev_b32_e32 v115, 16, v99
	v_and_b32_e32 v99, 0xffff0000, v99
	v_fmac_f32_e32 v115, v50, v54
	v_add_f32_e32 v50, v51, v83
	v_fmac_f32_e32 v99, v50, v49
	v_mul_f32_e32 v49, v98, v98
	v_mul_f32_e32 v50, v99, v99
	v_fmac_f32_e32 v49, v114, v114
	v_fmac_f32_e32 v50, v115, v115
	v_add_f32_e32 v49, v49, v50
	v_add_f32_e32 v54, v48, v49
	v_mov_b32_e32 v55, v54
	s_nop 1
	v_permlane16_swap_b32_e32 v55, v54
	v_lshl_add_u64 v[48:49], s[16:17], 0, v[90:91]
	v_lshl_add_u64 v[52:53], v[152:153], 1, v[48:49]
	v_cvt_pk_bf16_f32 v50, v110, v96
	v_cvt_pk_bf16_f32 v51, v112, v97
	s_waitcnt lgkmcnt(0)
	v_add_f32_e32 v48, v54, v55
	v_mov_b32_e32 v49, v48
	s_nop 1
	v_permlane32_swap_b32_e32 v49, v48
	v_mov_b32_e32 v204, v50
	v_mov_b32_e32 v205, v51
	v_cvt_pk_bf16_f32 v50, v114, v98
	v_cvt_pk_bf16_f32 v51, v115, v99
	v_mov_b32_e32 v206, v50
	v_mov_b32_e32 v207, v51
	v_lshl_add_u64 v[212:213], v[52:53], 0, v[214:215]
	s_nop 0
	v_permlane16_swap_b32_e32 v204, v206
	v_permlane16_swap_b32_e32 v205, v207
	global_store_dwordx4 v[212:213], v[204:207], off
	s_and_saveexec_b64 s[2:3], vcc
	s_cbranch_execz .LBB0_1539
	s_waitcnt lgkmcnt(0)
	v_add_f32_e32 v50, v48, v49
	v_lshlrev_b64 v[48:49], 8, v[78:79]
	v_lshl_add_u64 v[48:49], s[18:19], 0, v[48:49]
	v_lshl_add_u64 v[48:49], s[0:1], 2, v[48:49]
	s_lshl_b32 s22, s44, 2
	v_lshl_add_u64 v[48:49], v[48:49], 0, s[22:23]
	global_store_dword v[48:49], v50, off
.LBB0_1539:
	s_or_b64 exec, exec, s[2:3]
	v_add_f32_e32 v44, v44, v100
	v_mul_f32_e32 v44, 0xbfb8aa3b, v44
	v_exp_f32_e32 v44, v44
	v_add_f32_e32 v45, v45, v101
	v_mul_f32_e32 v45, 0xbfb8aa3b, v45
	v_exp_f32_e32 v45, v45
	v_add_f32_e32 v44, 1.0, v44
	v_rcp_f32_e32 v44, v44
	s_waitcnt vmcnt(7)
	v_lshlrev_b32_e32 v48, 16, v88
	v_add_f32_e32 v40, v40, v92
	s_waitcnt lgkmcnt(0)
	v_and_b32_e32 v49, 0xffff0000, v88
	v_fmac_f32_e32 v48, v40, v44
	v_add_f32_e32 v44, v46, v102
	v_add_f32_e32 v40, 1.0, v45
	v_mul_f32_e32 v44, 0xbfb8aa3b, v44
	v_add_f32_e32 v45, v47, v103
	v_rcp_f32_e32 v40, v40
	v_exp_f32_e32 v44, v44
	v_mul_f32_e32 v45, 0xbfb8aa3b, v45
	v_exp_f32_e32 v45, v45
	v_add_f32_e32 v41, v41, v93
	v_add_f32_e32 v36, v36, v84
	v_fmac_f32_e32 v49, v41, v40
	v_add_f32_e32 v40, 1.0, v44
	v_mul_f32_e32 v36, 0xbfb8aa3b, v36
	v_rcp_f32_e32 v40, v40
	v_add_f32_e32 v41, 1.0, v45
	v_exp_f32_e32 v36, v36
	v_rcp_f32_e32 v41, v41
	v_lshlrev_b32_e32 v50, 16, v89
	v_add_f32_e32 v42, v42, v94
	v_and_b32_e32 v51, 0xffff0000, v89
	v_fmac_f32_e32 v50, v42, v40
	v_add_f32_e32 v40, v43, v95
	v_add_f32_e32 v36, 1.0, v36
	v_add_f32_e32 v37, v37, v85
	v_fmac_f32_e32 v51, v40, v41
	v_rcp_f32_e32 v36, v36
	v_mul_f32_e32 v37, 0xbfb8aa3b, v37
	v_mul_f32_e32 v40, v49, v49
	v_mul_f32_e32 v41, v51, v51
	v_exp_f32_e32 v37, v37
	v_fmac_f32_e32 v40, v48, v48
	v_fmac_f32_e32 v41, v50, v50
	v_add_f32_e32 v40, v40, v41
	s_waitcnt vmcnt(6)
	v_lshlrev_b32_e32 v41, 16, v76
	v_add_f32_e32 v32, v32, v80
	v_fmac_f32_e32 v41, v32, v36
	v_add_f32_e32 v36, v38, v86
	v_add_f32_e32 v32, 1.0, v37
	v_mul_f32_e32 v36, 0xbfb8aa3b, v36
	v_add_f32_e32 v37, v39, v87
	v_rcp_f32_e32 v32, v32
	v_exp_f32_e32 v36, v36
	v_mul_f32_e32 v37, 0xbfb8aa3b, v37
	v_exp_f32_e32 v37, v37
	v_and_b32_e32 v42, 0xffff0000, v76
	v_add_f32_e32 v33, v33, v81
	v_fmac_f32_e32 v42, v33, v32
	v_add_f32_e32 v32, 1.0, v36
	v_rcp_f32_e32 v32, v32
	v_add_f32_e32 v33, 1.0, v37
	v_rcp_f32_e32 v33, v33
	v_lshlrev_b32_e32 v43, 16, v77
	v_add_f32_e32 v34, v34, v82
	v_and_b32_e32 v44, 0xffff0000, v77
	v_fmac_f32_e32 v43, v34, v32
	v_add_f32_e32 v32, v35, v83
	v_fmac_f32_e32 v44, v32, v33
	v_mul_f32_e32 v32, v42, v42
	v_mul_f32_e32 v33, v44, v44
	v_fmac_f32_e32 v32, v41, v41
	v_fmac_f32_e32 v33, v43, v43
	v_add_f32_e32 v32, v32, v33
	v_add_f32_e32 v38, v40, v32
	v_mov_b32_e32 v39, v38
	s_nop 1
	v_permlane16_swap_b32_e32 v39, v38
	v_lshl_add_u64 v[32:33], s[16:17], 0, v[74:75]
	v_lshl_add_u64 v[36:37], v[152:153], 1, v[32:33]
	v_cvt_pk_bf16_f32 v34, v48, v49
	v_cvt_pk_bf16_f32 v35, v50, v51
	s_waitcnt lgkmcnt(0)
	v_add_f32_e32 v32, v38, v39
	v_mov_b32_e32 v33, v32
	s_nop 1
	v_permlane32_swap_b32_e32 v33, v32
	v_mov_b32_e32 v208, v34
	v_mov_b32_e32 v209, v35
	v_cvt_pk_bf16_f32 v34, v41, v42
	v_cvt_pk_bf16_f32 v35, v43, v44
	v_mov_b32_e32 v210, v34
	v_mov_b32_e32 v211, v35
	v_lshl_add_u64 v[212:213], v[36:37], 0, v[214:215]
	s_nop 0
	v_permlane16_swap_b32_e32 v208, v210
	v_permlane16_swap_b32_e32 v209, v211
	global_store_dwordx4 v[212:213], v[208:211], off
	s_and_saveexec_b64 s[2:3], vcc
	s_cbranch_execz .LBB0_1541
	s_waitcnt lgkmcnt(0)
	v_add_f32_e32 v34, v32, v33
	v_lshlrev_b64 v[32:33], 8, v[70:71]
	v_lshl_add_u64 v[32:33], s[18:19], 0, v[32:33]
	v_lshl_add_u64 v[32:33], s[0:1], 2, v[32:33]
	s_lshl_b32 s22, s44, 2
	v_lshl_add_u64 v[32:33], v[32:33], 0, s[22:23]
	global_store_dword v[32:33], v34, off
.LBB0_1541:
	s_or_b64 exec, exec, s[2:3]
	v_add_f32_e32 v28, v28, v100
	v_mul_f32_e32 v28, 0xbfb8aa3b, v28
	v_exp_f32_e32 v28, v28
	v_add_f32_e32 v29, v29, v101
	v_mul_f32_e32 v29, 0xbfb8aa3b, v29
	v_exp_f32_e32 v29, v29
	v_add_f32_e32 v28, 1.0, v28
	v_rcp_f32_e32 v28, v28
	s_waitcnt vmcnt(7)
	v_lshlrev_b32_e32 v32, 16, v72
	v_add_f32_e32 v24, v24, v92
	s_waitcnt lgkmcnt(0)
	v_and_b32_e32 v33, 0xffff0000, v72
	v_fmac_f32_e32 v32, v24, v28
	v_add_f32_e32 v28, v30, v102
	v_add_f32_e32 v24, 1.0, v29
	v_mul_f32_e32 v28, 0xbfb8aa3b, v28
	v_add_f32_e32 v29, v31, v103
	v_rcp_f32_e32 v24, v24
	v_exp_f32_e32 v28, v28
	v_mul_f32_e32 v29, 0xbfb8aa3b, v29
	v_exp_f32_e32 v29, v29
	v_add_f32_e32 v25, v25, v93
	v_add_f32_e32 v20, v20, v84
	v_fmac_f32_e32 v33, v25, v24
	v_add_f32_e32 v24, 1.0, v28
	v_mul_f32_e32 v20, 0xbfb8aa3b, v20
	v_rcp_f32_e32 v24, v24
	v_add_f32_e32 v25, 1.0, v29
	v_exp_f32_e32 v20, v20
	v_rcp_f32_e32 v25, v25
	v_lshlrev_b32_e32 v34, 16, v73
	v_add_f32_e32 v26, v26, v94
	v_and_b32_e32 v35, 0xffff0000, v73
	v_fmac_f32_e32 v34, v26, v24
	v_add_f32_e32 v24, v27, v95
	v_add_f32_e32 v20, 1.0, v20
	v_add_f32_e32 v21, v21, v85
	v_fmac_f32_e32 v35, v24, v25
	v_rcp_f32_e32 v20, v20
	v_mul_f32_e32 v21, 0xbfb8aa3b, v21
	v_mul_f32_e32 v24, v33, v33
	v_mul_f32_e32 v25, v35, v35
	v_exp_f32_e32 v21, v21
	v_fmac_f32_e32 v24, v32, v32
	v_fmac_f32_e32 v25, v34, v34
	v_add_f32_e32 v24, v24, v25
	s_waitcnt vmcnt(6)
	v_lshlrev_b32_e32 v25, 16, v68
	v_add_f32_e32 v16, v16, v80
	v_fmac_f32_e32 v25, v16, v20
	v_add_f32_e32 v20, v22, v86
	v_add_f32_e32 v16, 1.0, v21
	v_mul_f32_e32 v20, 0xbfb8aa3b, v20
	v_add_f32_e32 v21, v23, v87
	v_rcp_f32_e32 v16, v16
	v_exp_f32_e32 v20, v20
	v_mul_f32_e32 v21, 0xbfb8aa3b, v21
	v_exp_f32_e32 v21, v21
	v_and_b32_e32 v26, 0xffff0000, v68
	v_add_f32_e32 v17, v17, v81
	v_fmac_f32_e32 v26, v17, v16
	v_add_f32_e32 v16, 1.0, v20
	v_rcp_f32_e32 v16, v16
	v_add_f32_e32 v17, 1.0, v21
	v_rcp_f32_e32 v17, v17
	v_lshlrev_b32_e32 v27, 16, v69
	v_add_f32_e32 v18, v18, v82
	v_and_b32_e32 v28, 0xffff0000, v69
	v_fmac_f32_e32 v27, v18, v16
	v_add_f32_e32 v16, v19, v83
	v_fmac_f32_e32 v28, v16, v17
	v_mul_f32_e32 v16, v26, v26
	v_mul_f32_e32 v17, v28, v28
	v_fmac_f32_e32 v16, v25, v25
	v_fmac_f32_e32 v17, v27, v27
	v_add_f32_e32 v16, v16, v17
	v_add_f32_e32 v22, v24, v16
	v_mov_b32_e32 v23, v22
	s_nop 1
	v_permlane16_swap_b32_e32 v23, v22
	v_lshl_add_u64 v[16:17], s[16:17], 0, v[62:63]
	v_lshl_add_u64 v[20:21], v[152:153], 1, v[16:17]
	v_cvt_pk_bf16_f32 v18, v32, v33
	v_cvt_pk_bf16_f32 v19, v34, v35
	s_waitcnt lgkmcnt(0)
	v_add_f32_e32 v16, v22, v23
	v_mov_b32_e32 v17, v16
	s_nop 1
	v_permlane32_swap_b32_e32 v17, v16
	v_mov_b32_e32 v204, v18
	v_mov_b32_e32 v205, v19
	v_cvt_pk_bf16_f32 v18, v25, v26
	v_cvt_pk_bf16_f32 v19, v27, v28
	v_mov_b32_e32 v206, v18
	v_mov_b32_e32 v207, v19
	v_lshl_add_u64 v[212:213], v[20:21], 0, v[214:215]
	s_nop 0
	v_permlane16_swap_b32_e32 v204, v206
	v_permlane16_swap_b32_e32 v205, v207
	global_store_dwordx4 v[212:213], v[204:207], off
	s_and_saveexec_b64 s[2:3], vcc
	s_cbranch_execz .LBB0_1543
	s_waitcnt lgkmcnt(0)
	v_add_f32_e32 v18, v16, v17
	v_lshlrev_b64 v[16:17], 8, v[66:67]
	v_lshl_add_u64 v[16:17], s[18:19], 0, v[16:17]
	v_lshl_add_u64 v[16:17], s[0:1], 2, v[16:17]
	s_lshl_b32 s22, s44, 2
	v_lshl_add_u64 v[16:17], v[16:17], 0, s[22:23]
	global_store_dword v[16:17], v18, off
.LBB0_1543:
	s_or_b64 exec, exec, s[2:3]
	v_add_f32_e32 v12, v12, v100
	v_mul_f32_e32 v12, 0xbfb8aa3b, v12
	v_exp_f32_e32 v12, v12
	v_add_f32_e32 v13, v13, v101
	v_mul_f32_e32 v13, 0xbfb8aa3b, v13
	v_exp_f32_e32 v13, v13
	v_add_f32_e32 v12, 1.0, v12
	v_rcp_f32_e32 v12, v12
	s_waitcnt vmcnt(7)
	v_lshlrev_b32_e32 v16, 16, v60
	v_add_f32_e32 v8, v8, v92
	s_waitcnt lgkmcnt(0)
	v_and_b32_e32 v17, 0xffff0000, v60
	v_fmac_f32_e32 v16, v8, v12
	v_add_f32_e32 v12, v14, v102
	v_add_f32_e32 v8, 1.0, v13
	v_mul_f32_e32 v12, 0xbfb8aa3b, v12
	v_add_f32_e32 v13, v15, v103
	v_rcp_f32_e32 v8, v8
	v_exp_f32_e32 v12, v12
	v_mul_f32_e32 v13, 0xbfb8aa3b, v13
	v_exp_f32_e32 v13, v13
	v_add_f32_e32 v9, v9, v93
	v_add_f32_e32 v4, v4, v84
	v_fmac_f32_e32 v17, v9, v8
	v_add_f32_e32 v8, 1.0, v12
	v_mul_f32_e32 v4, 0xbfb8aa3b, v4
	v_rcp_f32_e32 v8, v8
	v_add_f32_e32 v9, 1.0, v13
	v_exp_f32_e32 v4, v4
	v_rcp_f32_e32 v9, v9
	v_lshlrev_b32_e32 v18, 16, v61
	v_add_f32_e32 v10, v10, v94
	v_and_b32_e32 v19, 0xffff0000, v61
	v_fmac_f32_e32 v18, v10, v8
	v_add_f32_e32 v8, v11, v95
	v_add_f32_e32 v4, 1.0, v4
	v_add_f32_e32 v5, v5, v85
	v_fmac_f32_e32 v19, v8, v9
	v_rcp_f32_e32 v4, v4
	v_mul_f32_e32 v5, 0xbfb8aa3b, v5
	v_mul_f32_e32 v8, v17, v17
	v_mul_f32_e32 v9, v19, v19
	v_exp_f32_e32 v5, v5
	v_fmac_f32_e32 v8, v16, v16
	v_fmac_f32_e32 v9, v18, v18
	v_add_f32_e32 v8, v8, v9
	s_waitcnt vmcnt(6)
	v_lshlrev_b32_e32 v9, 16, v58
	v_add_f32_e32 v0, v0, v80
	v_fmac_f32_e32 v9, v0, v4
	v_add_f32_e32 v4, v6, v86
	v_add_f32_e32 v0, 1.0, v5
	v_mul_f32_e32 v4, 0xbfb8aa3b, v4
	v_add_f32_e32 v5, v7, v87
	v_rcp_f32_e32 v0, v0
	v_exp_f32_e32 v4, v4
	v_mul_f32_e32 v5, 0xbfb8aa3b, v5
	v_exp_f32_e32 v5, v5
	v_and_b32_e32 v10, 0xffff0000, v58
	v_add_f32_e32 v1, v1, v81
	v_fmac_f32_e32 v10, v1, v0
	v_add_f32_e32 v0, 1.0, v4
	v_rcp_f32_e32 v0, v0
	v_add_f32_e32 v1, 1.0, v5
	v_rcp_f32_e32 v1, v1
	v_lshlrev_b32_e32 v11, 16, v59
	v_add_f32_e32 v2, v2, v82
	v_and_b32_e32 v12, 0xffff0000, v59
	v_fmac_f32_e32 v11, v2, v0
	v_add_f32_e32 v0, v3, v83
	v_fmac_f32_e32 v12, v0, v1
	v_mul_f32_e32 v0, v10, v10
	v_mul_f32_e32 v1, v12, v12
	v_fmac_f32_e32 v0, v9, v9
	v_fmac_f32_e32 v1, v11, v11
	v_add_f32_e32 v0, v0, v1
	v_add_f32_e32 v6, v8, v0
	v_mov_b32_e32 v7, v6
	s_nop 1
	v_permlane16_swap_b32_e32 v7, v6
	v_lshl_add_u64 v[0:1], s[16:17], 0, v[56:57]
	v_lshl_add_u64 v[4:5], v[152:153], 1, v[0:1]
	v_cvt_pk_bf16_f32 v2, v16, v17
	v_cvt_pk_bf16_f32 v3, v18, v19
	s_waitcnt lgkmcnt(0)
	v_add_f32_e32 v0, v6, v7
	v_mov_b32_e32 v1, v0
	s_nop 1
	v_permlane32_swap_b32_e32 v1, v0
	v_mov_b32_e32 v208, v2
	v_mov_b32_e32 v209, v3
	v_cvt_pk_bf16_f32 v2, v9, v10
	v_cvt_pk_bf16_f32 v3, v11, v12
	v_mov_b32_e32 v210, v2
	v_mov_b32_e32 v211, v3
	v_lshl_add_u64 v[212:213], v[4:5], 0, v[214:215]
	s_nop 0
	v_permlane16_swap_b32_e32 v208, v210
	v_permlane16_swap_b32_e32 v209, v211
	global_store_dwordx4 v[212:213], v[208:211], off
	s_and_saveexec_b64 s[2:3], vcc
	s_cbranch_execz .LBB0_1545
	s_waitcnt lgkmcnt(0)
	v_add_f32_e32 v2, v0, v1
	v_lshlrev_b64 v[0:1], 8, v[64:65]
	v_lshl_add_u64 v[0:1], s[18:19], 0, v[0:1]
	v_lshl_add_u64 v[0:1], s[0:1], 2, v[0:1]
	s_lshl_b32 s22, s44, 2
	v_lshl_add_u64 v[0:1], v[0:1], 0, s[22:23]
	global_store_dword v[0:1], v2, off
